# FFN-in K-loop: in the two 6-DMA load sections keep 3 LDS-DMA issues and move 3 between the MFMAs of the following section (balanced split)
# baseline (speedup 1.0000x reference)
.LBB0_477:
	s_ashr_i32 s17, s16, 31
	s_lshl_b64 s[18:19], s[16:17], 19
	s_add_u32 s18, s0, s18
	s_addc_u32 s19, s1, s19
	s_and_b64 s[24:25], s[38:39], exec
	s_cselect_b32 s4, s19, s41
	s_cselect_b32 s9, s18, s40
	s_ashr_i32 s85, s84, 31
	s_lshl_b64 s[24:25], s[84:85], 19
	s_add_u32 s82, s80, s24
	s_addc_u32 s83, s81, s25
	s_and_b64 s[24:25], s[38:39], exec
	s_cselect_b32 s17, s83, s13
	s_cselect_b32 s24, s82, s12
	s_add_u32 s40, s40, 0x40080
	s_addc_u32 s41, s41, 0
	s_add_u32 s25, s12, 0x100
	s_addc_u32 s50, s13, 0
	s_mov_b32 s51, -2
	s_add_u32 s12, s40, 0xfffc0080
	s_addc_u32 s13, s41, -1
	s_add_i32 s85, 0, 0x10000
	s_cmp_eq_u32 s51, 12
	s_cselect_b32 s43, s4, s13
	s_cselect_b32 s42, s9, s12
	v_add_u32_e32 v158, s85, v196
	s_cselect_b32 s13, s17, s50
	s_cselect_b32 s12, s24, s25
	s_add_i32 s27, 0, 0x14000
	ds_read_b128 v[150:153], v158
	ds_read_b128 v[154:157], v158 offset:1024
	ds_read_b128 v[170:173], v158 offset:2048
	ds_read_b128 v[174:177], v158 offset:3072
	v_add_u32_e32 v158, s27, v196
	ds_read_b128 v[178:181], v158
	ds_read_b128 v[182:185], v158 offset:1024
	ds_read_b128 v[186:189], v158 offset:2048
	ds_read_b128 v[200:203], v158 offset:3072
	s_add_i32 m0, s15, 0xc000
	ds_read_b128 v[204:207], v199
	ds_read_b128 v[208:211], v199 offset:1024
	ds_read_b128 v[212:215], v199 offset:2048
	ds_read_b128 v[234:237], v199 offset:3072
	ds_read_b128 v[238:241], v199 offset:4096
	ds_read_b128 v[242:245], v199 offset:5120
	ds_read_b128 v[246:249], v199 offset:6144
	ds_read_b128 v[222:225], v199 offset:7168
	global_load_lds_dwordx4 v146, s[40:41]
	s_add_i32 m0, s15, 0xe000
	s_nop 0
	global_load_lds_dwordx4 v148, s[40:41]
	s_waitcnt vmcnt(8)
	s_waitcnt lgkmcnt(0)
	s_barrier
	s_setprio 1
	s_waitcnt lgkmcnt(0)
	v_mfma_f32_16x16x32_bf16 v[124:127], v[150:153], v[204:207], 0
	v_mfma_f32_16x16x32_bf16 v[120:123], v[170:173], v[204:207], 0
	v_mfma_f32_16x16x32_bf16 v[108:111], v[150:153], v[212:215], 0
	v_mfma_f32_16x16x32_bf16 v[104:107], v[170:173], v[212:215], 0
	v_mfma_f32_16x16x32_bf16 v[92:95], v[150:153], v[238:241], 0
	v_mfma_f32_16x16x32_bf16 v[88:91], v[170:173], v[238:241], 0
	v_mfma_f32_16x16x32_bf16 v[76:79], v[150:153], v[246:249], 0
	v_mfma_f32_16x16x32_bf16 v[72:75], v[170:173], v[246:249], 0
	v_mfma_f32_16x16x32_bf16 v[124:127], v[154:157], v[208:211], v[124:127]
	v_mfma_f32_16x16x32_bf16 v[120:123], v[174:177], v[208:211], v[120:123]
	v_mfma_f32_16x16x32_bf16 v[108:111], v[154:157], v[234:237], v[108:111]
	v_mfma_f32_16x16x32_bf16 v[104:107], v[174:177], v[234:237], v[104:107]
	v_mfma_f32_16x16x32_bf16 v[92:95], v[154:157], v[242:245], v[92:95]
	v_mfma_f32_16x16x32_bf16 v[88:91], v[174:177], v[242:245], v[88:91]
	v_mfma_f32_16x16x32_bf16 v[76:79], v[154:157], v[222:225], v[76:79]
	v_mfma_f32_16x16x32_bf16 v[72:75], v[174:177], v[222:225], v[72:75]
	v_mfma_f32_16x16x32_bf16 v[116:119], v[178:181], v[204:207], 0
	v_mfma_f32_16x16x32_bf16 v[112:115], v[186:189], v[204:207], 0
	v_mfma_f32_16x16x32_bf16 v[100:103], v[178:181], v[212:215], 0
	v_mfma_f32_16x16x32_bf16 v[96:99], v[186:189], v[212:215], 0
	v_mfma_f32_16x16x32_bf16 v[84:87], v[178:181], v[238:241], 0
	v_mfma_f32_16x16x32_bf16 v[80:83], v[186:189], v[238:241], 0
	v_mfma_f32_16x16x32_bf16 v[68:71], v[178:181], v[246:249], 0
	v_mfma_f32_16x16x32_bf16 v[64:67], v[186:189], v[246:249], 0
	v_mfma_f32_16x16x32_bf16 v[116:119], v[182:185], v[208:211], v[116:119]
	v_mfma_f32_16x16x32_bf16 v[112:115], v[200:203], v[208:211], v[112:115]
	v_mfma_f32_16x16x32_bf16 v[100:103], v[182:185], v[234:237], v[100:103]
	v_mfma_f32_16x16x32_bf16 v[96:99], v[200:203], v[234:237], v[96:99]
	v_mfma_f32_16x16x32_bf16 v[84:87], v[182:185], v[242:245], v[84:87]
	v_mfma_f32_16x16x32_bf16 v[80:83], v[200:203], v[242:245], v[80:83]
	v_mfma_f32_16x16x32_bf16 v[68:71], v[182:185], v[222:225], v[68:71]
	v_mfma_f32_16x16x32_bf16 v[64:67], v[200:203], v[222:225], v[64:67]
	s_setprio 0
	s_barrier
	s_add_i32 s85, s85, s86
	s_mov_b32 m0, s85
	ds_read_b128 v[204:207], v199 offset:16384
	ds_read_b128 v[208:211], v199 offset:17408
	ds_read_b128 v[212:215], v199 offset:18432
	ds_read_b128 v[222:225], v199 offset:19456
	ds_read_b128 v[234:237], v199 offset:20480
	ds_read_b128 v[238:241], v199 offset:21504
	ds_read_b128 v[242:245], v199 offset:22528
	ds_read_b128 v[246:249], v199 offset:23552
	global_load_lds_dwordx4 v130, s[12:13]
	s_add_i32 m0, s85, 0x2000
	s_add_u32 s98, s12, 0x40000
	s_addc_u32 s99, s13, 0
	s_add_i32 s27, s27, s86
	global_load_lds_dwordx4 v134, s[12:13]
	s_mov_b32 m0, s27
	s_nop 0
	global_load_lds_dwordx4 v130, s[98:99]
	s_waitcnt vmcnt(5)
	s_waitcnt lgkmcnt(0)
	s_barrier
	s_setprio 1
	s_waitcnt lgkmcnt(0)
	v_mfma_f32_16x16x32_bf16 v[60:63], v[150:153], v[204:207], 0
	v_mfma_f32_16x16x32_bf16 v[56:59], v[170:173], v[204:207], 0
	v_mfma_f32_16x16x32_bf16 v[44:47], v[150:153], v[212:215], 0
	v_mfma_f32_16x16x32_bf16 v[40:43], v[170:173], v[212:215], 0
	v_mfma_f32_16x16x32_bf16 v[28:31], v[150:153], v[234:237], 0
	v_mfma_f32_16x16x32_bf16 v[24:27], v[170:173], v[234:237], 0
	v_mfma_f32_16x16x32_bf16 v[12:15], v[150:153], v[242:245], 0
	v_mfma_f32_16x16x32_bf16 v[8:11], v[170:173], v[242:245], 0
	s_add_i32 m0, s27, 0x2000
	s_nop 0
	global_load_lds_dwordx4 v134, s[98:99]
	v_mfma_f32_16x16x32_bf16 v[60:63], v[154:157], v[208:211], v[60:63]
	v_mfma_f32_16x16x32_bf16 v[56:59], v[174:177], v[208:211], v[56:59]
	v_mfma_f32_16x16x32_bf16 v[44:47], v[154:157], v[222:225], v[44:47]
	v_mfma_f32_16x16x32_bf16 v[40:43], v[174:177], v[222:225], v[40:43]
	v_mfma_f32_16x16x32_bf16 v[28:31], v[154:157], v[238:241], v[28:31]
	v_mfma_f32_16x16x32_bf16 v[24:27], v[174:177], v[238:241], v[24:27]
	v_mfma_f32_16x16x32_bf16 v[12:15], v[154:157], v[246:249], v[12:15]
	v_mfma_f32_16x16x32_bf16 v[8:11], v[174:177], v[246:249], v[8:11]
	s_mov_b32 m0, s15
	s_nop 0
	global_load_lds_dwordx4 v128, s[42:43]
	v_mfma_f32_16x16x32_bf16 v[52:55], v[178:181], v[204:207], 0
	v_mfma_f32_16x16x32_bf16 v[48:51], v[186:189], v[204:207], 0
	v_mfma_f32_16x16x32_bf16 v[36:39], v[178:181], v[212:215], 0
	v_mfma_f32_16x16x32_bf16 v[32:35], v[186:189], v[212:215], 0
	v_mfma_f32_16x16x32_bf16 v[20:23], v[178:181], v[234:237], 0
	v_mfma_f32_16x16x32_bf16 v[16:19], v[186:189], v[234:237], 0
	v_mfma_f32_16x16x32_bf16 v[4:7], v[178:181], v[242:245], 0
	v_mfma_f32_16x16x32_bf16 v[0:3], v[186:189], v[242:245], 0
	s_mov_b32 m0, s87
	s_nop 0
	global_load_lds_dwordx4 v132, s[42:43]
	v_mfma_f32_16x16x32_bf16 v[52:55], v[182:185], v[208:211], v[52:55]
	v_mfma_f32_16x16x32_bf16 v[48:51], v[200:203], v[208:211], v[48:51]
	v_mfma_f32_16x16x32_bf16 v[36:39], v[182:185], v[222:225], v[36:39]
	v_mfma_f32_16x16x32_bf16 v[32:35], v[200:203], v[222:225], v[32:35]
	v_mfma_f32_16x16x32_bf16 v[20:23], v[182:185], v[238:241], v[20:23]
	v_mfma_f32_16x16x32_bf16 v[16:19], v[200:203], v[238:241], v[16:19]
	v_mfma_f32_16x16x32_bf16 v[4:7], v[182:185], v[246:249], v[4:7]
	v_mfma_f32_16x16x32_bf16 v[0:3], v[200:203], v[246:249], v[0:3]
	s_setprio 0
	s_barrier
	s_add_i32 s27, 0, 0x18000
	v_add_u32_e32 v160, s27, v196
	s_add_i32 s85, 0, 0x1c000
	ds_read_b128 v[150:153], v160
	ds_read_b128 v[154:157], v160 offset:1024
	ds_read_b128 v[170:173], v160 offset:2048
	ds_read_b128 v[174:177], v160 offset:3072
	v_add_u32_e32 v160, s85, v196
	ds_read_b128 v[178:181], v160
	ds_read_b128 v[182:185], v160 offset:1024
	ds_read_b128 v[186:189], v160 offset:2048
	ds_read_b128 v[200:203], v160 offset:3072
	s_add_u32 s42, s42, 0x40000
	s_addc_u32 s43, s43, 0
	s_mov_b32 m0, s88
	ds_read_b128 v[204:207], v199 offset:32768
	ds_read_b128 v[208:211], v199 offset:33792
	ds_read_b128 v[212:215], v199 offset:34816
	ds_read_b128 v[222:225], v199 offset:35840
	ds_read_b128 v[234:237], v199 offset:36864
	ds_read_b128 v[238:241], v199 offset:37888
	ds_read_b128 v[242:245], v199 offset:38912
	ds_read_b128 v[246:249], v199 offset:39936
	global_load_lds_dwordx4 v128, s[42:43]
	s_mov_b32 m0, s89
	s_nop 0
	global_load_lds_dwordx4 v132, s[42:43]
	s_waitcnt vmcnt(8)
	s_waitcnt lgkmcnt(0)
	s_barrier
	s_setprio 1
	s_waitcnt lgkmcnt(0)
	v_mfma_f32_16x16x32_bf16 v[124:127], v[150:153], v[204:207], v[124:127]
	v_mfma_f32_16x16x32_bf16 v[120:123], v[170:173], v[204:207], v[120:123]
	v_mfma_f32_16x16x32_bf16 v[108:111], v[150:153], v[212:215], v[108:111]
	v_mfma_f32_16x16x32_bf16 v[104:107], v[170:173], v[212:215], v[104:107]
	v_mfma_f32_16x16x32_bf16 v[92:95], v[150:153], v[234:237], v[92:95]
	v_mfma_f32_16x16x32_bf16 v[88:91], v[170:173], v[234:237], v[88:91]
	v_mfma_f32_16x16x32_bf16 v[76:79], v[150:153], v[242:245], v[76:79]
	v_mfma_f32_16x16x32_bf16 v[72:75], v[170:173], v[242:245], v[72:75]
	v_mfma_f32_16x16x32_bf16 v[124:127], v[154:157], v[208:211], v[124:127]
	v_mfma_f32_16x16x32_bf16 v[120:123], v[174:177], v[208:211], v[120:123]
	v_mfma_f32_16x16x32_bf16 v[108:111], v[154:157], v[222:225], v[108:111]
	v_mfma_f32_16x16x32_bf16 v[104:107], v[174:177], v[222:225], v[104:107]
	v_mfma_f32_16x16x32_bf16 v[92:95], v[154:157], v[238:241], v[92:95]
	v_mfma_f32_16x16x32_bf16 v[88:91], v[174:177], v[238:241], v[88:91]
	v_mfma_f32_16x16x32_bf16 v[76:79], v[154:157], v[246:249], v[76:79]
	v_mfma_f32_16x16x32_bf16 v[72:75], v[174:177], v[246:249], v[72:75]
	v_mfma_f32_16x16x32_bf16 v[116:119], v[178:181], v[204:207], v[116:119]
	v_mfma_f32_16x16x32_bf16 v[112:115], v[186:189], v[204:207], v[112:115]
	v_mfma_f32_16x16x32_bf16 v[100:103], v[178:181], v[212:215], v[100:103]
	v_mfma_f32_16x16x32_bf16 v[96:99], v[186:189], v[212:215], v[96:99]
	v_mfma_f32_16x16x32_bf16 v[84:87], v[178:181], v[234:237], v[84:87]
	v_mfma_f32_16x16x32_bf16 v[80:83], v[186:189], v[234:237], v[80:83]
	v_mfma_f32_16x16x32_bf16 v[68:71], v[178:181], v[242:245], v[68:71]
	v_mfma_f32_16x16x32_bf16 v[64:67], v[186:189], v[242:245], v[64:67]
	v_mfma_f32_16x16x32_bf16 v[116:119], v[182:185], v[208:211], v[116:119]
	v_mfma_f32_16x16x32_bf16 v[112:115], v[200:203], v[208:211], v[112:115]
	v_mfma_f32_16x16x32_bf16 v[100:103], v[182:185], v[222:225], v[100:103]
	v_mfma_f32_16x16x32_bf16 v[96:99], v[200:203], v[222:225], v[96:99]
	v_mfma_f32_16x16x32_bf16 v[84:87], v[182:185], v[238:241], v[84:87]
	v_mfma_f32_16x16x32_bf16 v[80:83], v[200:203], v[238:241], v[80:83]
	v_mfma_f32_16x16x32_bf16 v[68:71], v[182:185], v[246:249], v[68:71]
	v_mfma_f32_16x16x32_bf16 v[64:67], v[200:203], v[246:249], v[64:67]
	s_setprio 0
	s_barrier
	s_add_i32 s27, s27, s86
	s_add_u32 s100, s12, 0x80
	s_addc_u32 s101, s13, 0
	s_mov_b32 m0, s27
	ds_read_b128 v[204:207], v199 offset:49152
	ds_read_b128 v[208:211], v199 offset:50176
	ds_read_b128 v[212:215], v199 offset:51200
	ds_read_b128 v[222:225], v199 offset:52224
	ds_read_b128 v[234:237], v199 offset:53248
	ds_read_b128 v[238:241], v199 offset:54272
	ds_read_b128 v[242:245], v199 offset:55296
	ds_read_b128 v[246:249], v199 offset:56320
	global_load_lds_dwordx4 v130, s[100:101]
	s_add_i32 m0, s27, 0x2000
	s_add_u32 s12, s12, 0x40080
	s_addc_u32 s13, s13, 0
	s_add_i32 s27, s85, s86
	global_load_lds_dwordx4 v134, s[100:101]
	s_mov_b32 m0, s27
	s_nop 0
	global_load_lds_dwordx4 v130, s[12:13]
	s_waitcnt vmcnt(5)
	s_waitcnt lgkmcnt(0)
	s_barrier
	s_setprio 1
	s_waitcnt lgkmcnt(0)
	v_mfma_f32_16x16x32_bf16 v[60:63], v[150:153], v[204:207], v[60:63]
	v_mfma_f32_16x16x32_bf16 v[56:59], v[170:173], v[204:207], v[56:59]
	v_mfma_f32_16x16x32_bf16 v[44:47], v[150:153], v[212:215], v[44:47]
	v_mfma_f32_16x16x32_bf16 v[40:43], v[170:173], v[212:215], v[40:43]
	v_mfma_f32_16x16x32_bf16 v[28:31], v[150:153], v[234:237], v[28:31]
	v_mfma_f32_16x16x32_bf16 v[24:27], v[170:173], v[234:237], v[24:27]
	v_mfma_f32_16x16x32_bf16 v[12:15], v[150:153], v[242:245], v[12:15]
	v_mfma_f32_16x16x32_bf16 v[8:11], v[170:173], v[242:245], v[8:11]
	s_add_i32 m0, s27, 0x2000
	s_nop 0
	global_load_lds_dwordx4 v134, s[12:13]
	v_mfma_f32_16x16x32_bf16 v[60:63], v[154:157], v[208:211], v[60:63]
	v_mfma_f32_16x16x32_bf16 v[56:59], v[174:177], v[208:211], v[56:59]
	v_mfma_f32_16x16x32_bf16 v[44:47], v[154:157], v[222:225], v[44:47]
	v_mfma_f32_16x16x32_bf16 v[40:43], v[174:177], v[222:225], v[40:43]
	v_mfma_f32_16x16x32_bf16 v[28:31], v[154:157], v[238:241], v[28:31]
	v_mfma_f32_16x16x32_bf16 v[24:27], v[174:177], v[238:241], v[24:27]
	v_mfma_f32_16x16x32_bf16 v[12:15], v[154:157], v[246:249], v[12:15]
	v_mfma_f32_16x16x32_bf16 v[8:11], v[174:177], v[246:249], v[8:11]
	s_add_u32 s98, s42, 0xfffc0080
	s_addc_u32 s99, s43, -1
	s_mov_b32 m0, s92
	s_nop 0
	global_load_lds_dwordx4 v128, s[98:99]
	v_mfma_f32_16x16x32_bf16 v[52:55], v[178:181], v[204:207], v[52:55]
	v_mfma_f32_16x16x32_bf16 v[48:51], v[186:189], v[204:207], v[48:51]
	v_mfma_f32_16x16x32_bf16 v[36:39], v[178:181], v[212:215], v[36:39]
	v_mfma_f32_16x16x32_bf16 v[32:35], v[186:189], v[212:215], v[32:35]
	v_mfma_f32_16x16x32_bf16 v[20:23], v[178:181], v[234:237], v[20:23]
	v_mfma_f32_16x16x32_bf16 v[16:19], v[186:189], v[234:237], v[16:19]
	v_mfma_f32_16x16x32_bf16 v[4:7], v[178:181], v[242:245], v[4:7]
	v_mfma_f32_16x16x32_bf16 v[0:3], v[186:189], v[242:245], v[0:3]
	s_mov_b32 m0, s93
	s_nop 0
	global_load_lds_dwordx4 v132, s[98:99]
	v_mfma_f32_16x16x32_bf16 v[52:55], v[182:185], v[208:211], v[52:55]
	v_mfma_f32_16x16x32_bf16 v[48:51], v[200:203], v[208:211], v[48:51]
	v_mfma_f32_16x16x32_bf16 v[36:39], v[182:185], v[222:225], v[36:39]
	v_mfma_f32_16x16x32_bf16 v[32:35], v[200:203], v[222:225], v[32:35]
	v_mfma_f32_16x16x32_bf16 v[20:23], v[182:185], v[238:241], v[20:23]
	v_mfma_f32_16x16x32_bf16 v[16:19], v[200:203], v[238:241], v[16:19]
	v_mfma_f32_16x16x32_bf16 v[4:7], v[182:185], v[246:249], v[4:7]
	v_mfma_f32_16x16x32_bf16 v[0:3], v[200:203], v[246:249], v[0:3]
	s_setprio 0
	s_barrier
	s_add_i32 s51, s51, 2
	s_add_u32 s40, s40, 0x100
	s_addc_u32 s41, s41, 0
	s_add_u32 s25, s25, 0x100
	s_addc_u32 s50, s50, 0
	s_cmp_gt_u32 s51, 13
.LBB0_478:
	s_add_u32 s12, s40, 0xfffc0080
	s_addc_u32 s13, s41, -1
	s_add_i32 s85, 0, 0x10000
	s_cmp_eq_u32 s51, 12
	s_cselect_b32 s43, s4, s13
	s_cselect_b32 s42, s9, s12
	v_add_u32_e32 v158, s85, v196
	s_cselect_b32 s13, s17, s50
	s_cselect_b32 s12, s24, s25
	s_add_i32 s27, 0, 0x14000
	ds_read_b128 v[150:153], v158
	ds_read_b128 v[154:157], v158 offset:1024
	ds_read_b128 v[170:173], v158 offset:2048
	ds_read_b128 v[174:177], v158 offset:3072
	v_add_u32_e32 v158, s27, v196
	ds_read_b128 v[178:181], v158
	ds_read_b128 v[182:185], v158 offset:1024
	ds_read_b128 v[186:189], v158 offset:2048
	ds_read_b128 v[200:203], v158 offset:3072
	s_add_i32 m0, s15, 0xc000
	ds_read_b128 v[204:207], v199
	ds_read_b128 v[208:211], v199 offset:1024
	ds_read_b128 v[212:215], v199 offset:2048
	ds_read_b128 v[234:237], v199 offset:3072
	ds_read_b128 v[238:241], v199 offset:4096
	ds_read_b128 v[242:245], v199 offset:5120
	ds_read_b128 v[246:249], v199 offset:6144
	ds_read_b128 v[222:225], v199 offset:7168
	global_load_lds_dwordx4 v146, s[40:41]
	s_add_i32 m0, s15, 0xe000
	s_nop 0
	global_load_lds_dwordx4 v148, s[40:41]
	s_waitcnt vmcnt(8)
	s_waitcnt lgkmcnt(0)
	s_barrier
	s_setprio 1
	s_waitcnt lgkmcnt(0)
	v_mfma_f32_16x16x32_bf16 v[124:127], v[150:153], v[204:207], v[124:127]
	v_mfma_f32_16x16x32_bf16 v[120:123], v[170:173], v[204:207], v[120:123]
	v_mfma_f32_16x16x32_bf16 v[108:111], v[150:153], v[212:215], v[108:111]
	v_mfma_f32_16x16x32_bf16 v[104:107], v[170:173], v[212:215], v[104:107]
	v_mfma_f32_16x16x32_bf16 v[92:95], v[150:153], v[238:241], v[92:95]
	v_mfma_f32_16x16x32_bf16 v[88:91], v[170:173], v[238:241], v[88:91]
	v_mfma_f32_16x16x32_bf16 v[76:79], v[150:153], v[246:249], v[76:79]
	v_mfma_f32_16x16x32_bf16 v[72:75], v[170:173], v[246:249], v[72:75]
	v_mfma_f32_16x16x32_bf16 v[124:127], v[154:157], v[208:211], v[124:127]
	v_mfma_f32_16x16x32_bf16 v[120:123], v[174:177], v[208:211], v[120:123]
	v_mfma_f32_16x16x32_bf16 v[108:111], v[154:157], v[234:237], v[108:111]
	v_mfma_f32_16x16x32_bf16 v[104:107], v[174:177], v[234:237], v[104:107]
	v_mfma_f32_16x16x32_bf16 v[92:95], v[154:157], v[242:245], v[92:95]
	v_mfma_f32_16x16x32_bf16 v[88:91], v[174:177], v[242:245], v[88:91]
	v_mfma_f32_16x16x32_bf16 v[76:79], v[154:157], v[222:225], v[76:79]
	v_mfma_f32_16x16x32_bf16 v[72:75], v[174:177], v[222:225], v[72:75]
	v_mfma_f32_16x16x32_bf16 v[116:119], v[178:181], v[204:207], v[116:119]
	v_mfma_f32_16x16x32_bf16 v[112:115], v[186:189], v[204:207], v[112:115]
	v_mfma_f32_16x16x32_bf16 v[100:103], v[178:181], v[212:215], v[100:103]
	v_mfma_f32_16x16x32_bf16 v[96:99], v[186:189], v[212:215], v[96:99]
	v_mfma_f32_16x16x32_bf16 v[84:87], v[178:181], v[238:241], v[84:87]
	v_mfma_f32_16x16x32_bf16 v[80:83], v[186:189], v[238:241], v[80:83]
	v_mfma_f32_16x16x32_bf16 v[68:71], v[178:181], v[246:249], v[68:71]
	v_mfma_f32_16x16x32_bf16 v[64:67], v[186:189], v[246:249], v[64:67]
	v_mfma_f32_16x16x32_bf16 v[116:119], v[182:185], v[208:211], v[116:119]
	v_mfma_f32_16x16x32_bf16 v[112:115], v[200:203], v[208:211], v[112:115]
	v_mfma_f32_16x16x32_bf16 v[100:103], v[182:185], v[234:237], v[100:103]
	v_mfma_f32_16x16x32_bf16 v[96:99], v[200:203], v[234:237], v[96:99]
	v_mfma_f32_16x16x32_bf16 v[84:87], v[182:185], v[242:245], v[84:87]
	v_mfma_f32_16x16x32_bf16 v[80:83], v[200:203], v[242:245], v[80:83]
	v_mfma_f32_16x16x32_bf16 v[68:71], v[182:185], v[222:225], v[68:71]
	v_mfma_f32_16x16x32_bf16 v[64:67], v[200:203], v[222:225], v[64:67]
	s_setprio 0
	s_barrier
	s_add_i32 s85, s85, s86
	s_mov_b32 m0, s85
	ds_read_b128 v[204:207], v199 offset:16384
	ds_read_b128 v[208:211], v199 offset:17408
	ds_read_b128 v[212:215], v199 offset:18432
	ds_read_b128 v[222:225], v199 offset:19456
	ds_read_b128 v[234:237], v199 offset:20480
	ds_read_b128 v[238:241], v199 offset:21504
	ds_read_b128 v[242:245], v199 offset:22528
	ds_read_b128 v[246:249], v199 offset:23552
	global_load_lds_dwordx4 v130, s[12:13]
	s_add_i32 m0, s85, 0x2000
	s_add_u32 s98, s12, 0x40000
	s_addc_u32 s99, s13, 0
	s_add_i32 s27, s27, s86
	global_load_lds_dwordx4 v134, s[12:13]
	s_mov_b32 m0, s27
	s_nop 0
	global_load_lds_dwordx4 v130, s[98:99]
	s_waitcnt vmcnt(5)
	s_waitcnt lgkmcnt(0)
	s_barrier
	s_setprio 1
	s_waitcnt lgkmcnt(0)
	v_mfma_f32_16x16x32_bf16 v[60:63], v[150:153], v[204:207], v[60:63]
	v_mfma_f32_16x16x32_bf16 v[56:59], v[170:173], v[204:207], v[56:59]
	v_mfma_f32_16x16x32_bf16 v[44:47], v[150:153], v[212:215], v[44:47]
	v_mfma_f32_16x16x32_bf16 v[40:43], v[170:173], v[212:215], v[40:43]
	v_mfma_f32_16x16x32_bf16 v[28:31], v[150:153], v[234:237], v[28:31]
	v_mfma_f32_16x16x32_bf16 v[24:27], v[170:173], v[234:237], v[24:27]
	v_mfma_f32_16x16x32_bf16 v[12:15], v[150:153], v[242:245], v[12:15]
	v_mfma_f32_16x16x32_bf16 v[8:11], v[170:173], v[242:245], v[8:11]
	s_add_i32 m0, s27, 0x2000
	s_nop 0
	global_load_lds_dwordx4 v134, s[98:99]
	v_mfma_f32_16x16x32_bf16 v[60:63], v[154:157], v[208:211], v[60:63]
	v_mfma_f32_16x16x32_bf16 v[56:59], v[174:177], v[208:211], v[56:59]
	v_mfma_f32_16x16x32_bf16 v[44:47], v[154:157], v[222:225], v[44:47]
	v_mfma_f32_16x16x32_bf16 v[40:43], v[174:177], v[222:225], v[40:43]
	v_mfma_f32_16x16x32_bf16 v[28:31], v[154:157], v[238:241], v[28:31]
	v_mfma_f32_16x16x32_bf16 v[24:27], v[174:177], v[238:241], v[24:27]
	v_mfma_f32_16x16x32_bf16 v[12:15], v[154:157], v[246:249], v[12:15]
	v_mfma_f32_16x16x32_bf16 v[8:11], v[174:177], v[246:249], v[8:11]
	s_mov_b32 m0, s15
	s_nop 0
	global_load_lds_dwordx4 v128, s[42:43]
	v_mfma_f32_16x16x32_bf16 v[52:55], v[178:181], v[204:207], v[52:55]
	v_mfma_f32_16x16x32_bf16 v[48:51], v[186:189], v[204:207], v[48:51]
	v_mfma_f32_16x16x32_bf16 v[36:39], v[178:181], v[212:215], v[36:39]
	v_mfma_f32_16x16x32_bf16 v[32:35], v[186:189], v[212:215], v[32:35]
	v_mfma_f32_16x16x32_bf16 v[20:23], v[178:181], v[234:237], v[20:23]
	v_mfma_f32_16x16x32_bf16 v[16:19], v[186:189], v[234:237], v[16:19]
	v_mfma_f32_16x16x32_bf16 v[4:7], v[178:181], v[242:245], v[4:7]
	v_mfma_f32_16x16x32_bf16 v[0:3], v[186:189], v[242:245], v[0:3]
	s_mov_b32 m0, s87
	s_nop 0
	global_load_lds_dwordx4 v132, s[42:43]
	v_mfma_f32_16x16x32_bf16 v[52:55], v[182:185], v[208:211], v[52:55]
	v_mfma_f32_16x16x32_bf16 v[48:51], v[200:203], v[208:211], v[48:51]
	v_mfma_f32_16x16x32_bf16 v[36:39], v[182:185], v[222:225], v[36:39]
	v_mfma_f32_16x16x32_bf16 v[32:35], v[200:203], v[222:225], v[32:35]
	v_mfma_f32_16x16x32_bf16 v[20:23], v[182:185], v[238:241], v[20:23]
	v_mfma_f32_16x16x32_bf16 v[16:19], v[200:203], v[238:241], v[16:19]
	v_mfma_f32_16x16x32_bf16 v[4:7], v[182:185], v[246:249], v[4:7]
	v_mfma_f32_16x16x32_bf16 v[0:3], v[200:203], v[246:249], v[0:3]
	s_setprio 0
	s_barrier
	s_add_i32 s27, 0, 0x18000
	v_add_u32_e32 v160, s27, v196
	s_add_i32 s85, 0, 0x1c000
	ds_read_b128 v[150:153], v160
	ds_read_b128 v[154:157], v160 offset:1024
	ds_read_b128 v[170:173], v160 offset:2048
	ds_read_b128 v[174:177], v160 offset:3072
	v_add_u32_e32 v160, s85, v196
	ds_read_b128 v[178:181], v160
	ds_read_b128 v[182:185], v160 offset:1024
	ds_read_b128 v[186:189], v160 offset:2048
	ds_read_b128 v[200:203], v160 offset:3072
	s_add_u32 s42, s42, 0x40000
	s_addc_u32 s43, s43, 0
	s_mov_b32 m0, s88
	ds_read_b128 v[204:207], v199 offset:32768
	ds_read_b128 v[208:211], v199 offset:33792
	ds_read_b128 v[212:215], v199 offset:34816
	ds_read_b128 v[222:225], v199 offset:35840
	ds_read_b128 v[234:237], v199 offset:36864
	ds_read_b128 v[238:241], v199 offset:37888
	ds_read_b128 v[242:245], v199 offset:38912
	ds_read_b128 v[246:249], v199 offset:39936
	global_load_lds_dwordx4 v128, s[42:43]
	s_mov_b32 m0, s89
	s_nop 0
	global_load_lds_dwordx4 v132, s[42:43]
	s_waitcnt vmcnt(8)
	s_waitcnt lgkmcnt(0)
	s_barrier
	s_setprio 1
	s_waitcnt lgkmcnt(0)
	v_mfma_f32_16x16x32_bf16 v[124:127], v[150:153], v[204:207], v[124:127]
	v_mfma_f32_16x16x32_bf16 v[120:123], v[170:173], v[204:207], v[120:123]
	v_mfma_f32_16x16x32_bf16 v[108:111], v[150:153], v[212:215], v[108:111]
	v_mfma_f32_16x16x32_bf16 v[104:107], v[170:173], v[212:215], v[104:107]
	v_mfma_f32_16x16x32_bf16 v[92:95], v[150:153], v[234:237], v[92:95]
	v_mfma_f32_16x16x32_bf16 v[88:91], v[170:173], v[234:237], v[88:91]
	v_mfma_f32_16x16x32_bf16 v[76:79], v[150:153], v[242:245], v[76:79]
	v_mfma_f32_16x16x32_bf16 v[72:75], v[170:173], v[242:245], v[72:75]
	v_mfma_f32_16x16x32_bf16 v[124:127], v[154:157], v[208:211], v[124:127]
	v_mfma_f32_16x16x32_bf16 v[120:123], v[174:177], v[208:211], v[120:123]
	v_mfma_f32_16x16x32_bf16 v[108:111], v[154:157], v[222:225], v[108:111]
	v_mfma_f32_16x16x32_bf16 v[104:107], v[174:177], v[222:225], v[104:107]
	v_mfma_f32_16x16x32_bf16 v[92:95], v[154:157], v[238:241], v[92:95]
	v_mfma_f32_16x16x32_bf16 v[88:91], v[174:177], v[238:241], v[88:91]
	v_mfma_f32_16x16x32_bf16 v[76:79], v[154:157], v[246:249], v[76:79]
	v_mfma_f32_16x16x32_bf16 v[72:75], v[174:177], v[246:249], v[72:75]
	v_mfma_f32_16x16x32_bf16 v[116:119], v[178:181], v[204:207], v[116:119]
	v_mfma_f32_16x16x32_bf16 v[112:115], v[186:189], v[204:207], v[112:115]
	v_mfma_f32_16x16x32_bf16 v[100:103], v[178:181], v[212:215], v[100:103]
	v_mfma_f32_16x16x32_bf16 v[96:99], v[186:189], v[212:215], v[96:99]
	v_mfma_f32_16x16x32_bf16 v[84:87], v[178:181], v[234:237], v[84:87]
	v_mfma_f32_16x16x32_bf16 v[80:83], v[186:189], v[234:237], v[80:83]
	v_mfma_f32_16x16x32_bf16 v[68:71], v[178:181], v[242:245], v[68:71]
	v_mfma_f32_16x16x32_bf16 v[64:67], v[186:189], v[242:245], v[64:67]
	v_mfma_f32_16x16x32_bf16 v[116:119], v[182:185], v[208:211], v[116:119]
	v_mfma_f32_16x16x32_bf16 v[112:115], v[200:203], v[208:211], v[112:115]
	v_mfma_f32_16x16x32_bf16 v[100:103], v[182:185], v[222:225], v[100:103]
	v_mfma_f32_16x16x32_bf16 v[96:99], v[200:203], v[222:225], v[96:99]
	v_mfma_f32_16x16x32_bf16 v[84:87], v[182:185], v[238:241], v[84:87]
	v_mfma_f32_16x16x32_bf16 v[80:83], v[200:203], v[238:241], v[80:83]
	v_mfma_f32_16x16x32_bf16 v[68:71], v[182:185], v[246:249], v[68:71]
	v_mfma_f32_16x16x32_bf16 v[64:67], v[200:203], v[246:249], v[64:67]
	s_setprio 0
	s_barrier
	s_add_i32 s27, s27, s86
	s_add_u32 s100, s12, 0x80
	s_addc_u32 s101, s13, 0
	s_mov_b32 m0, s27
	ds_read_b128 v[204:207], v199 offset:49152
	ds_read_b128 v[208:211], v199 offset:50176
	ds_read_b128 v[212:215], v199 offset:51200
	ds_read_b128 v[222:225], v199 offset:52224
	ds_read_b128 v[234:237], v199 offset:53248
	ds_read_b128 v[238:241], v199 offset:54272
	ds_read_b128 v[242:245], v199 offset:55296
	ds_read_b128 v[246:249], v199 offset:56320
	global_load_lds_dwordx4 v130, s[100:101]
	s_add_i32 m0, s27, 0x2000
	s_add_u32 s12, s12, 0x40080
	s_addc_u32 s13, s13, 0
	s_add_i32 s27, s85, s86
	global_load_lds_dwordx4 v134, s[100:101]
	s_mov_b32 m0, s27
	s_nop 0
	global_load_lds_dwordx4 v130, s[12:13]
	s_waitcnt vmcnt(5)
	s_waitcnt lgkmcnt(0)
	s_barrier
	s_setprio 1
	s_waitcnt lgkmcnt(0)
	v_mfma_f32_16x16x32_bf16 v[60:63], v[150:153], v[204:207], v[60:63]
	v_mfma_f32_16x16x32_bf16 v[56:59], v[170:173], v[204:207], v[56:59]
	v_mfma_f32_16x16x32_bf16 v[44:47], v[150:153], v[212:215], v[44:47]
	v_mfma_f32_16x16x32_bf16 v[40:43], v[170:173], v[212:215], v[40:43]
	v_mfma_f32_16x16x32_bf16 v[28:31], v[150:153], v[234:237], v[28:31]
	v_mfma_f32_16x16x32_bf16 v[24:27], v[170:173], v[234:237], v[24:27]
	v_mfma_f32_16x16x32_bf16 v[12:15], v[150:153], v[242:245], v[12:15]
	v_mfma_f32_16x16x32_bf16 v[8:11], v[170:173], v[242:245], v[8:11]
	s_add_i32 m0, s27, 0x2000
	s_nop 0
	global_load_lds_dwordx4 v134, s[12:13]
	v_mfma_f32_16x16x32_bf16 v[60:63], v[154:157], v[208:211], v[60:63]
	v_mfma_f32_16x16x32_bf16 v[56:59], v[174:177], v[208:211], v[56:59]
	v_mfma_f32_16x16x32_bf16 v[44:47], v[154:157], v[222:225], v[44:47]
	v_mfma_f32_16x16x32_bf16 v[40:43], v[174:177], v[222:225], v[40:43]
	v_mfma_f32_16x16x32_bf16 v[28:31], v[154:157], v[238:241], v[28:31]
	v_mfma_f32_16x16x32_bf16 v[24:27], v[174:177], v[238:241], v[24:27]
	v_mfma_f32_16x16x32_bf16 v[12:15], v[154:157], v[246:249], v[12:15]
	v_mfma_f32_16x16x32_bf16 v[8:11], v[174:177], v[246:249], v[8:11]
	s_add_u32 s98, s42, 0xfffc0080
	s_addc_u32 s99, s43, -1
	s_mov_b32 m0, s92
	s_nop 0
	global_load_lds_dwordx4 v128, s[98:99]
	v_mfma_f32_16x16x32_bf16 v[52:55], v[178:181], v[204:207], v[52:55]
	v_mfma_f32_16x16x32_bf16 v[48:51], v[186:189], v[204:207], v[48:51]
	v_mfma_f32_16x16x32_bf16 v[36:39], v[178:181], v[212:215], v[36:39]
	v_mfma_f32_16x16x32_bf16 v[32:35], v[186:189], v[212:215], v[32:35]
	v_mfma_f32_16x16x32_bf16 v[20:23], v[178:181], v[234:237], v[20:23]
	v_mfma_f32_16x16x32_bf16 v[16:19], v[186:189], v[234:237], v[16:19]
	v_mfma_f32_16x16x32_bf16 v[4:7], v[178:181], v[242:245], v[4:7]
	v_mfma_f32_16x16x32_bf16 v[0:3], v[186:189], v[242:245], v[0:3]
	s_mov_b32 m0, s93
	s_nop 0
	global_load_lds_dwordx4 v132, s[98:99]
	v_mfma_f32_16x16x32_bf16 v[52:55], v[182:185], v[208:211], v[52:55]
	v_mfma_f32_16x16x32_bf16 v[48:51], v[200:203], v[208:211], v[48:51]
	v_mfma_f32_16x16x32_bf16 v[36:39], v[182:185], v[222:225], v[36:39]
	v_mfma_f32_16x16x32_bf16 v[32:35], v[200:203], v[222:225], v[32:35]
	v_mfma_f32_16x16x32_bf16 v[20:23], v[182:185], v[238:241], v[20:23]
	v_mfma_f32_16x16x32_bf16 v[16:19], v[200:203], v[238:241], v[16:19]
	v_mfma_f32_16x16x32_bf16 v[4:7], v[182:185], v[246:249], v[4:7]
	v_mfma_f32_16x16x32_bf16 v[0:3], v[200:203], v[246:249], v[0:3]
	s_setprio 0
	s_barrier
	s_add_i32 s51, s51, 2
	s_add_u32 s40, s40, 0x100
	s_addc_u32 s41, s41, 0
	s_add_u32 s25, s25, 0x100
	s_addc_u32 s50, s50, 0
	s_cmp_gt_u32 s51, 13
	s_cbranch_scc0 .LBB0_478
	s_and_b64 vcc, exec, s[10:11]
	s_cbranch_vccz .LBB0_481
	s_barrier
